# attn loop: QK segment opens with MFMAs on the prefetched K fragments (no VALU head); s_nop padding before the row-max replaced by the V fragment reads
# baseline (speedup 1.0000x reference)
; __device__ __forceinline__ void partialSM(f32x16& p0, f32x16& p1, float& m_reg, float& mn, float& alpha) {
;     ...
;   for (int r = 0; r < 16; ++r) p0[r] = __builtin_amdgcn_exp2f(p0[r]);
; }
; __device__ __forceinline__ void finishSM(f32x16& p0, f32x16& p1, float alpha, float& l_reg, bf16x8& pa0, bf16x8& pa1, bf16x8& pa2, bf16x8& pa3) {
; #pragma unroll
;   for (int r = 0; r < 16; ++r) p1[r] = __builtin_amdgcn_exp2f(p1[r]);
;   float ps = 0;
; #pragma unroll
;   for (int r = 0; r < 16; ++r) ps += p0[r];
; #pragma unroll
;   for (int r = 0; r < 16; ++r) ps += p1[r];
;   { auto rr = __builtin_amdgcn_permlane32_swap(__float_as_uint(ps), __float_as_uint(ps), false, false);
;     ps = __uint_as_float(rr[0]) + __uint_as_float(rr[1]); }
;   l_reg = l_reg * alpha + ps;
;     ...
;   PK4(p0, 0, pa0); PK4(p0, 8, pa1); PK4(p1, 0, pa2); PK4(p1, 8, pa3);
;     ...
; }
; __device__ __forceinline__ void qkt(f32x16& p0, f32x16& p1, const char* Ks, const bf16x8* qr, const char* qrl, int r32, int hi) {
;   p0 = f32x16{}; p1 = f32x16{};
; #pragma unroll
;   for (int d0 = 0; d0 < 8; ++d0) { int cb = (d0 * 16 + hi * 8) * 2;
;     bf16x8 b0 = *reinterpret_cast<const bf16x8*>(Ks + KSWZ(r32, cb));
;     bf16x8 b1 = *reinterpret_cast<const bf16x8*>(Ks + KSWZ(32 + r32, cb));
;     p0 = __builtin_amdgcn_mfma_f32_32x32x16_bf16(b0, qr[d0], p0, 0, 0, 0);
;     p1 = __builtin_amdgcn_mfma_f32_32x32x16_bf16(b1, qr[d0], p1, 0, 0, 0); }
; #pragma unroll
;   for (int d0 = 8; d0 < 12; ++d0) { int cb = (d0 * 16 + hi * 8) * 2;
;     bf16x8 b0 = *reinterpret_cast<const bf16x8*>(Ks + KSWZ(r32, cb));
;     bf16x8 b1 = *reinterpret_cast<const bf16x8*>(Ks + KSWZ(32 + r32, cb));
;     bf16x8 qf = *reinterpret_cast<const bf16x8*>(qrl + (((2 * (d0 - 8) + hi) ^ ((r32 >> 1) & 7)) << 4));
;     p0 = __builtin_amdgcn_mfma_f32_32x32x16_bf16(b0, qf, p0, 0, 0, 0);
;     p1 = __builtin_amdgcn_mfma_f32_32x32x16_bf16(b1, qf, p1, 0, 0, 0); }
; }
.LBB0_1151:
	s_sub_i32 s30, s76, 1
	s_cmp_eq_u32 s76, 0
	s_cselect_b32 s30, 2, s30
	s_add_i32 s18, s76, 1
	s_cmp_lg_u32 s76, 2
	s_cselect_b32 s18, s18, 0
	ds_read_b128 v[232:235], v199 offset:36864
	ds_read_b128 v[236:239], v199 offset:49152
	ds_read_b128 v[240:243], v205 offset:36864
	ds_read_b128 v[248:251], v205 offset:49152
	ds_read_b128 v[244:247], v206 offset:36864
	s_waitcnt lgkmcnt(3)
	v_mfma_f32_32x32x16_bf16 v[80:95], v[232:235], v[124:127], 0
	ds_read_b128 v[232:235], v206 offset:49152
	v_exp_f32_e32 v162, v162
	v_add_f32_e32 v211, v225, v228
	v_exp_f32_e32 v163, v163
	v_add_f32_e32 v211, v226, v211
	v_mfma_f32_32x32x16_bf16 v[64:79], v[236:239], v[124:127], 0
	ds_read_b128 v[236:239], v208 offset:36864
	v_exp_f32_e32 v160, v160
	v_add_f32_e32 v211, v229, v211
	v_exp_f32_e32 v161, v161
	v_add_f32_e32 v211, v227, v211
	s_waitcnt lgkmcnt(3)
	v_mfma_f32_32x32x16_bf16 v[80:95], v[240:243], v[120:123], v[80:95]
	ds_read_b128 v[240:243], v208 offset:49152
	v_exp_f32_e32 v158, v158
	v_add_f32_e32 v211, v230, v211
	v_exp_f32_e32 v159, v159
	v_add_f32_e32 v211, v223, v211
	v_mfma_f32_32x32x16_bf16 v[64:79], v[248:251], v[120:123], v[64:79]
	ds_read_b128 v[248:251], v207 offset:36864
	v_exp_f32_e32 v156, v156
	v_add_f32_e32 v211, v224, v211
	v_exp_f32_e32 v157, v157
	v_add_f32_e32 v211, v219, v211
	s_waitcnt lgkmcnt(3)
	v_mfma_f32_32x32x16_bf16 v[80:95], v[244:247], v[116:119], v[80:95]
	ds_read_b128 v[244:247], v207 offset:49152
	v_exp_f32_e32 v154, v154
	v_add_f32_e32 v211, v221, v211
	v_exp_f32_e32 v155, v155
	v_add_f32_e32 v211, v220, v211
	v_mfma_f32_32x32x16_bf16 v[64:79], v[232:235], v[116:119], v[64:79]
	ds_read_b128 v[232:235], v204 offset:36864
	v_exp_f32_e32 v152, v152
	v_add_f32_e32 v211, v222, v211
	v_exp_f32_e32 v153, v153
	v_add_f32_e32 v211, v215, v211
	s_waitcnt lgkmcnt(3)
	v_mfma_f32_32x32x16_bf16 v[80:95], v[236:239], v[112:115], v[80:95]
	ds_read_b128 v[236:239], v204 offset:49152
	v_exp_f32_e32 v150, v150
	v_add_f32_e32 v211, v217, v211
	v_exp_f32_e32 v151, v151
	v_add_f32_e32 v211, v216, v211
	v_mfma_f32_32x32x16_bf16 v[64:79], v[240:243], v[112:115], v[64:79]
	ds_read_b128 v[240:243], v203 offset:36864
	v_exp_f32_e32 v148, v148
	v_add_f32_e32 v211, v218, v211
	v_exp_f32_e32 v149, v149
	v_add_f32_e32 v212, v162, v163
	s_waitcnt lgkmcnt(3)
	v_mfma_f32_32x32x16_bf16 v[80:95], v[248:251], v[108:111], v[80:95]
	ds_read_b128 v[248:251], v203 offset:49152
	v_add_f32_e32 v212, v160, v212
	v_add_f32_e32 v212, v161, v212
	v_add_f32_e32 v212, v158, v212
	v_add_f32_e32 v212, v159, v212
	v_add_f32_e32 v212, v156, v212
	v_add_f32_e32 v212, v157, v212
	v_mfma_f32_32x32x16_bf16 v[64:79], v[244:247], v[108:111], v[64:79]
	ds_read_b128 v[244:247], v200 offset:36864
	v_add_f32_e32 v212, v154, v212
	v_add_f32_e32 v212, v155, v212
	v_add_f32_e32 v212, v152, v212
	v_add_f32_e32 v212, v153, v212
	v_add_f32_e32 v212, v150, v212
	v_add_f32_e32 v212, v151, v212
	s_waitcnt lgkmcnt(3)
	v_mfma_f32_32x32x16_bf16 v[80:95], v[232:235], v[104:107], v[80:95]
	ds_read_b128 v[232:235], v200 offset:49152
	v_add_f32_e32 v212, v148, v212
	v_add_f32_e32 v212, v149, v212
	v_add_f32_e32 v211, v211, v212
	v_mov_b32_e32 v212, v211
	s_lshl_b32 s19, s18, 14
	v_add_u32_e32 v231, s19, v183
	s_waitcnt vmcnt(0)
	ds_write_b128 v231, v[140:143]
	v_add_u32_e32 v140, s19, v184
	v_mfma_f32_32x32x16_bf16 v[64:79], v[236:239], v[104:107], v[64:79]
	ds_read_b128 v[236:239], v191 offset:36864
	ds_write_b128 v140, v[144:147]
	ds_write_b128 v185, v[136:139] offset:12288
	ds_write_b128 v185, v[132:135] offset:24576
	s_mov_b32 s18, 0xfffa0000
	ds_write_b128 v186, v[128:131] offset:12288
	v_add_co_u32_e32 v128, vcc, s18, v168
	s_mov_b32 s18, 0xfffc0000
	s_nop 0
	v_addc_co_u32_e32 v129, vcc, -1, v169, vcc
	s_waitcnt lgkmcnt(8)
	v_mfma_f32_32x32x16_bf16 v[80:95], v[240:243], v[100:103], v[80:95]
	ds_read_b128 v[240:243], v202 offset:49152
	v_add_co_u32_e32 v130, vcc, s18, v168
	s_movk_i32 s18, 0xe000
	s_nop 0
	v_addc_co_u32_e32 v131, vcc, -1, v169, vcc
	global_load_dwordx4 v[140:143], v[128:129], off
	global_load_dwordx4 v[136:139], v[128:129], off offset:-256
	global_load_dwordx4 v[144:147], v[130:131], off
	global_load_dwordx4 v[132:135], v[130:131], off offset:-256
	v_mfma_f32_32x32x16_bf16 v[64:79], v[248:251], v[100:103], v[64:79]
	ds_read_b128 v[248:251], v182
	v_add_co_u32_e32 v128, vcc, s18, v166
	s_nop 1
	v_addc_co_u32_e32 v129, vcc, -1, v167, vcc
	global_load_dwordx4 v[128:131], v[128:129], off
	v_cvt_pk_bf16_f32 v158, v158, v159
	v_cvt_pk_bf16_f32 v159, v156, v157
	v_permlane32_swap_b32_e32 v211, v212
	s_waitcnt lgkmcnt(8)
; __device__ __forceinline__ void finishSM(f32x16& p0, f32x16& p1, float alpha, float& l_reg, bf16x8& pa0, bf16x8& pa1, bf16x8& pa2, bf16x8& pa3) {
;     ...
;   PK4(p0, 0, pa0); PK4(p0, 8, pa1); PK4(p1, 0, pa2); PK4(p1, 8, pa3);
;     ...
; }
; __device__ __forceinline__ void qkt(f32x16& p0, f32x16& p1, const char* Ks, const bf16x8* qr, const char* qrl, int r32, int hi) {
;   p0 = f32x16{}; p1 = f32x16{};
; #pragma unroll
;   for (int d0 = 0; d0 < 8; ++d0) { int cb = (d0 * 16 + hi * 8) * 2;
;     bf16x8 b0 = *reinterpret_cast<const bf16x8*>(Ks + KSWZ(r32, cb));
;     bf16x8 b1 = *reinterpret_cast<const bf16x8*>(Ks + KSWZ(32 + r32, cb));
;     p0 = __builtin_amdgcn_mfma_f32_32x32x16_bf16(b0, qr[d0], p0, 0, 0, 0);
;     p1 = __builtin_amdgcn_mfma_f32_32x32x16_bf16(b1, qr[d0], p1, 0, 0, 0); }
; #pragma unroll
;   for (int d0 = 8; d0 < 12; ++d0) { int cb = (d0 * 16 + hi * 8) * 2;
;     bf16x8 b0 = *reinterpret_cast<const bf16x8*>(Ks + KSWZ(r32, cb));
;     bf16x8 b1 = *reinterpret_cast<const bf16x8*>(Ks + KSWZ(32 + r32, cb));
;     bf16x8 qf = *reinterpret_cast<const bf16x8*>(qrl + (((2 * (d0 - 8) + hi) ^ ((r32 >> 1) & 7)) << 4));
;     p0 = __builtin_amdgcn_mfma_f32_32x32x16_bf16(b0, qf, p0, 0, 0, 0);
;     p1 = __builtin_amdgcn_mfma_f32_32x32x16_bf16(b1, qf, p1, 0, 0, 0); }
; }
; __device__ __forceinline__ int v_st(int k, int c) { const int kk = (k & ~0xC) | ((k & 4) << 1) | ((k & 8) >> 1); return ((kk >> 3) * 4 + (c >> 5)) * 512 + ((kk & 7) * 32 + (c & 31)) * 2; }
; __device__ __forceinline__ int v_rd_base(int lane) { return ((lane & 3) << 3) | (((lane >> 2) & 3) << 6) | (((lane >> 4) & 1) << 5) | (((lane >> 5) & 1) << 8); }
; template <int OFF> __device__ __forceinline__ s16x4 tr_read(int vb) {
;   s16x4 r; asm volatile("ds_read_b64_tr_b16 %0, %1 offset:%2" : "=&v"(r) : "v"(vb), "i"(OFF) : "memory"); return r;
; }
; template <int D0> __device__ __forceinline__ void pv_one(f32x16& od, int vb, bf16x8 pa0, bf16x8 pa1, bf16x8 pa2, bf16x8 pa3) {
;   const s16x4 l0 = tr_read<v_rd_off(D0, 0, 0)>(vb), h0 = tr_read<v_rd_off(D0, 0, 1)>(vb), l1 = tr_read<v_rd_off(D0, 1, 0)>(vb), h1 = tr_read<v_rd_off(D0, 1, 1)>(vb);
;   const s16x4 l2 = tr_read<v_rd_off(D0, 2, 0)>(vb), h2 = tr_read<v_rd_off(D0, 2, 1)>(vb), l3 = tr_read<v_rd_off(D0, 3, 0)>(vb), h3 = tr_read<v_rd_off(D0, 3, 1)>(vb);
;   asm volatile("s_waitcnt lgkmcnt(0)" ::: "memory"); SBAR();
	v_mfma_f32_32x32x16_bf16 v[80:95], v[244:247], v[96:99], v[80:95]
	ds_read_b128 v[244:247], v198 offset:36864
	v_cvt_pk_bf16_f32 v156, v162, v163
	v_cvt_pk_bf16_f32 v157, v160, v161
	v_cvt_pk_bf16_f32 v160, v154, v155
	v_cvt_pk_bf16_f32 v161, v152, v153
	v_cvt_pk_bf16_f32 v162, v150, v151
	v_cvt_pk_bf16_f32 v163, v148, v149
	v_mfma_f32_32x32x16_bf16 v[64:79], v[232:235], v[96:99], v[64:79]
	ds_read_b128 v[232:235], v201 offset:49152
	v_add_f32_e32 v211, v211, v212
	v_cvt_pk_bf16_f32 v148, v225, v228
	v_cvt_pk_bf16_f32 v149, v226, v229
	v_cvt_pk_bf16_f32 v150, v227, v230
	v_cvt_pk_bf16_f32 v151, v223, v224
	v_cvt_pk_bf16_f32 v152, v219, v221
	s_waitcnt lgkmcnt(2)
	v_mfma_f32_32x32x16_bf16 v[80:95], v[236:239], v[248:251], v[80:95]
	ds_read_b128 v[236:239], v181
	v_cvt_pk_bf16_f32 v153, v220, v222
	v_cvt_pk_bf16_f32 v154, v215, v217
	v_cvt_pk_bf16_f32 v155, v216, v218
	v_fma_f32 v176, v209, v176, v211
	v_mfma_f32_32x32x16_bf16 v[64:79], v[240:243], v[248:251], v[64:79]
	ds_read_b128 v[240:243], v187 offset:36864
	ds_read_b128 v[248:251], v189 offset:49152
	s_waitcnt lgkmcnt(2)
	v_mfma_f32_32x32x16_bf16 v[80:95], v[244:247], v[236:239], v[80:95]
	ds_read_b128 v[244:247], v179
	v_mfma_f32_32x32x16_bf16 v[64:79], v[232:235], v[236:239], v[64:79]
	ds_read_b128 v[232:235], v188 offset:36864
	ds_read_b128 v[236:239], v190 offset:49152
	s_waitcnt lgkmcnt(2)
	v_mfma_f32_32x32x16_bf16 v[80:95], v[240:243], v[244:247], v[80:95]
	ds_read_b128 v[240:243], v177
	v_mfma_f32_32x32x16_bf16 v[64:79], v[248:251], v[244:247], v[64:79]
	s_waitcnt lgkmcnt(0)
	v_mfma_f32_32x32x16_bf16 v[80:95], v[232:235], v[240:243], v[80:95]
	v_mfma_f32_32x32x16_bf16 v[64:79], v[236:239], v[240:243], v[64:79]
	s_lshl_b32 s31, s30, 14
	v_add_u32_e32 v180, s31, v178
	ds_read_b64_tr_b16 v[232:233], v180 offset:0
	ds_read_b64_tr_b16 v[234:235], v180 offset:2048
	ds_read_b64_tr_b16 v[236:237], v180 offset:512
	ds_read_b64_tr_b16 v[238:239], v180 offset:2560
	ds_read_b64_tr_b16 v[240:241], v180 offset:1024
	ds_read_b64_tr_b16 v[242:243], v180 offset:3072
	ds_read_b64_tr_b16 v[248:249], v180 offset:1536
	ds_read_b64_tr_b16 v[250:251], v180 offset:3584
	ds_read_b64_tr_b16 v[244:245], v180 offset:4096
	ds_read_b64_tr_b16 v[246:247], v180 offset:6144
	v_max3_f32 v194, v80, v81, v82
	v_max3_f32 v195, v64, v65, v66
	v_max3_f32 v194, v194, v83, v84
	v_max3_f32 v195, v195, v67, v68
	s_waitcnt lgkmcnt(6)
	v_mfma_f32_32x32x16_bf16 v[32:47], v[148:151], v[232:235], v[32:47]
	ds_read_b64_tr_b16 v[232:233], v180 offset:4608
	ds_read_b64_tr_b16 v[234:235], v180 offset:6656
	v_max3_f32 v194, v194, v85, v86
	v_max3_f32 v195, v195, v69, v70
	v_max3_f32 v194, v194, v87, v88
	v_max3_f32 v195, v195, v71, v72
	v_mfma_f32_32x32x16_bf16 v[48:63], v[148:151], v[236:239], v[48:63]
	ds_read_b64_tr_b16 v[236:237], v180 offset:5120
	ds_read_b64_tr_b16 v[238:239], v180 offset:7168
	v_max3_f32 v194, v194, v89, v90
	v_max3_f32 v195, v195, v73, v74
	v_max3_f32 v194, v194, v91, v92
	v_max3_f32 v195, v195, v75, v76
	s_waitcnt lgkmcnt(6)
	v_mfma_f32_32x32x16_bf16 v[16:31], v[148:151], v[240:243], v[16:31]
	ds_read_b64_tr_b16 v[240:241], v180 offset:5632
	ds_read_b64_tr_b16 v[242:243], v180 offset:7680
	v_max3_f32 v194, v194, v93, v94
	v_max3_f32 v195, v195, v77, v78
	v_max3_f32 v194, v194, v95, v195
	v_max_f32_e32 v194, v194, v79
	v_mfma_f32_32x32x16_bf16 v[0:15], v[148:151], v[248:251], v[0:15]
	ds_read_b64_tr_b16 v[248:249], v180 offset:8192
	ds_read_b64_tr_b16 v[250:251], v180 offset:10240
	v_mov_b32_e32 v195, v194
	s_nop 1
	v_permlane32_swap_b32_e32 v194, v195
	v_max_f32_e32 v194, v194, v195
	s_waitcnt lgkmcnt(6)
	v_mfma_f32_32x32x16_bf16 v[32:47], v[152:155], v[244:247], v[32:47]
	ds_read_b64_tr_b16 v[244:245], v180 offset:8704
	ds_read_b64_tr_b16 v[246:247], v180 offset:10752
	v_sub_f32_e32 v195, v194, v210
	v_cmp_ge_f32_e32 vcc, s15, v195
	v_mfma_f32_32x32x16_bf16 v[48:63], v[152:155], v[232:235], v[48:63]
	ds_read_b64_tr_b16 v[232:233], v180 offset:9216
	ds_read_b64_tr_b16 v[234:235], v180 offset:11264
	s_cmp_eq_u64 vcc, exec
	s_cselect_b64 s[40:41], -1, 0
	s_cbranch_scc1 .Lattn_fast1p
	v_max_f32_e32 v194, v210, v194
	v_sub_f32_e32 v195, v210, v194
	v_mul_f32_e32 v195, 0x3dd53b94, v195
	v_exp_f32_e32 v214, v195
	v_mov_b32_e32 v210, v194
	s_branch .Lattn_join1p

; __device__ __forceinline__ void partialSM(f32x16& p0, f32x16& p1, float& m_reg, float& mn, float& alpha) {
;     ...
;   for (int r = 0; r < 16; ++r) p0[r] = __builtin_amdgcn_exp2f(p0[r]);
; }
; __device__ __forceinline__ void finishSM(f32x16& p0, f32x16& p1, float alpha, float& l_reg, bf16x8& pa0, bf16x8& pa1, bf16x8& pa2, bf16x8& pa3) {
; #pragma unroll
;   for (int r = 0; r < 16; ++r) p1[r] = __builtin_amdgcn_exp2f(p1[r]);
;   float ps = 0;
; #pragma unroll
;   for (int r = 0; r < 16; ++r) ps += p0[r];
; #pragma unroll
;   for (int r = 0; r < 16; ++r) ps += p1[r];
;   { auto rr = __builtin_amdgcn_permlane32_swap(__float_as_uint(ps), __float_as_uint(ps), false, false);
;     ps = __uint_as_float(rr[0]) + __uint_as_float(rr[1]); }
;   l_reg = l_reg * alpha + ps;
;     ...
;   PK4(p0, 0, pa0); PK4(p0, 8, pa1); PK4(p1, 0, pa2); PK4(p1, 8, pa3);
;     ...
; }
; __device__ __forceinline__ void qkt(f32x16& p0, f32x16& p1, const char* Ks, const bf16x8* qr, const char* qrl, int r32, int hi) {
;   p0 = f32x16{}; p1 = f32x16{};
; #pragma unroll
;   for (int d0 = 0; d0 < 8; ++d0) { int cb = (d0 * 16 + hi * 8) * 2;
;     bf16x8 b0 = *reinterpret_cast<const bf16x8*>(Ks + KSWZ(r32, cb));
;     bf16x8 b1 = *reinterpret_cast<const bf16x8*>(Ks + KSWZ(32 + r32, cb));
;     p0 = __builtin_amdgcn_mfma_f32_32x32x16_bf16(b0, qr[d0], p0, 0, 0, 0);
;     p1 = __builtin_amdgcn_mfma_f32_32x32x16_bf16(b1, qr[d0], p1, 0, 0, 0); }
; #pragma unroll
;   for (int d0 = 8; d0 < 12; ++d0) { int cb = (d0 * 16 + hi * 8) * 2;
;     bf16x8 b0 = *reinterpret_cast<const bf16x8*>(Ks + KSWZ(r32, cb));
;     bf16x8 b1 = *reinterpret_cast<const bf16x8*>(Ks + KSWZ(32 + r32, cb));
;     bf16x8 qf = *reinterpret_cast<const bf16x8*>(qrl + (((2 * (d0 - 8) + hi) ^ ((r32 >> 1) & 7)) << 4));
;     p0 = __builtin_amdgcn_mfma_f32_32x32x16_bf16(b0, qf, p0, 0, 0, 0);
;     p1 = __builtin_amdgcn_mfma_f32_32x32x16_bf16(b1, qf, p1, 0, 0, 0); }
; }
; __device__ __forceinline__ void attn_unit(const bf16_t* __restrict__ Qb, const bf16_t* __restrict__ Kn, const bf16_t* __restrict__ Vh, const bf16_t* __restrict__ Kr,
;                                           bf16_t* GO, int seq, char* lds, const int tid) {
;     ...
;   f32x16 pA0, pA1, pB0, pB1; float mnA, mnB, alA, alB; bf16x8 pa0, pa1, pa2, pa3; const int NT = seq / KVBLK;
;     ...
;   SLOAD(0, 0); SWRITE(0, 0); SLOAD(0, KVBLK); LBAR();
.Lattn_skip_rs1p:
	s_waitcnt lgkmcnt(3)
	v_mfma_f32_32x32x16_bf16 v[80:95], v[236:239], v[124:127], 0
	ds_read_b128 v[236:239], v206 offset:24576
	v_exp_f32_e32 v225, v225
	v_exp_f32_e32 v228, v228
	v_exp_f32_e32 v226, v226
	v_mfma_f32_32x32x16_bf16 v[64:79], v[240:243], v[124:127], 0
	ds_read_b128 v[240:243], v208 offset:12288
	v_add_f32_e32 v211, v225, v228
	v_exp_f32_e32 v229, v229
	v_add_f32_e32 v211, v226, v211
	v_exp_f32_e32 v227, v227
	s_waitcnt lgkmcnt(3)
	v_mfma_f32_32x32x16_bf16 v[80:95], v[248:251], v[120:123], v[80:95]
	ds_read_b128 v[248:251], v208 offset:24576
	v_add_f32_e32 v211, v229, v211
	v_exp_f32_e32 v230, v230
	v_add_f32_e32 v211, v227, v211
	v_exp_f32_e32 v223, v223
	v_mfma_f32_32x32x16_bf16 v[64:79], v[244:247], v[120:123], v[64:79]
	ds_read_b128 v[244:247], v207 offset:12288
	v_add_f32_e32 v211, v230, v211
	v_exp_f32_e32 v224, v224
	v_add_f32_e32 v211, v223, v211
	v_exp_f32_e32 v219, v219
	s_waitcnt lgkmcnt(3)
	v_mfma_f32_32x32x16_bf16 v[80:95], v[232:235], v[116:119], v[80:95]
	ds_read_b128 v[232:235], v207 offset:24576
	v_add_f32_e32 v211, v224, v211
	v_exp_f32_e32 v221, v221
	v_add_f32_e32 v211, v219, v211
	v_exp_f32_e32 v220, v220
	v_mfma_f32_32x32x16_bf16 v[64:79], v[236:239], v[116:119], v[64:79]
	ds_read_b128 v[236:239], v204 offset:12288
	v_add_f32_e32 v211, v221, v211
	v_exp_f32_e32 v222, v222
	v_add_f32_e32 v211, v220, v211
	v_exp_f32_e32 v215, v215
	s_waitcnt lgkmcnt(3)
	v_mfma_f32_32x32x16_bf16 v[80:95], v[240:243], v[112:115], v[80:95]
	ds_read_b128 v[240:243], v204 offset:24576
	v_add_f32_e32 v211, v222, v211
	v_exp_f32_e32 v217, v217
	v_add_f32_e32 v211, v215, v211
	v_exp_f32_e32 v216, v216
	v_mfma_f32_32x32x16_bf16 v[64:79], v[248:251], v[112:115], v[64:79]
	ds_read_b128 v[248:251], v203 offset:12288
	v_add_f32_e32 v211, v217, v211
	v_exp_f32_e32 v218, v218
	v_add_f32_e32 v211, v216, v211
	v_exp_f32_e32 v162, v162
	s_waitcnt lgkmcnt(3)
	v_mfma_f32_32x32x16_bf16 v[80:95], v[244:247], v[108:111], v[80:95]
	ds_read_b128 v[244:247], v203 offset:24576
	v_add_f32_e32 v211, v218, v211
	v_exp_f32_e32 v163, v163
	v_exp_f32_e32 v160, v160
	v_mfma_f32_32x32x16_bf16 v[64:79], v[232:235], v[108:111], v[64:79]
	ds_read_b128 v[232:235], v200 offset:12288
	v_exp_f32_e32 v161, v161
	v_exp_f32_e32 v158, v158
	v_exp_f32_e32 v159, v159
	s_waitcnt lgkmcnt(3)
	v_mfma_f32_32x32x16_bf16 v[80:95], v[236:239], v[104:107], v[80:95]
	ds_read_b128 v[236:239], v200 offset:24576
	v_exp_f32_e32 v156, v156
	v_exp_f32_e32 v157, v157
	v_exp_f32_e32 v154, v154
	v_mfma_f32_32x32x16_bf16 v[64:79], v[240:243], v[104:107], v[64:79]
	ds_read_b128 v[240:243], v191 offset:12288
	v_exp_f32_e32 v155, v155
	v_exp_f32_e32 v152, v152
	v_exp_f32_e32 v153, v153
	s_waitcnt lgkmcnt(3)
	v_mfma_f32_32x32x16_bf16 v[80:95], v[248:251], v[100:103], v[80:95]
	ds_read_b128 v[248:251], v202 offset:24576
	v_exp_f32_e32 v150, v150
	v_exp_f32_e32 v151, v151
	v_exp_f32_e32 v148, v148
	v_mfma_f32_32x32x16_bf16 v[64:79], v[244:247], v[100:103], v[64:79]
	ds_read_b128 v[244:247], v182
	v_exp_f32_e32 v149, v149
	v_add_f32_e32 v212, v162, v163
	v_add_f32_e32 v212, v160, v212
	v_add_f32_e32 v212, v161, v212
	v_add_f32_e32 v212, v158, v212
	s_waitcnt lgkmcnt(3)
	v_mfma_f32_32x32x16_bf16 v[80:95], v[232:235], v[96:99], v[80:95]
	ds_read_b128 v[232:235], v198 offset:12288
	v_add_f32_e32 v212, v159, v212
	v_add_f32_e32 v212, v156, v212
	v_add_f32_e32 v212, v157, v212
	v_add_f32_e32 v212, v154, v212
	v_add_f32_e32 v212, v155, v212
	v_add_f32_e32 v212, v152, v212
	v_mfma_f32_32x32x16_bf16 v[64:79], v[236:239], v[96:99], v[64:79]
	ds_read_b128 v[236:239], v201 offset:24576
	v_add_f32_e32 v212, v153, v212
	v_add_f32_e32 v212, v150, v212
	v_add_f32_e32 v212, v151, v212
	v_add_f32_e32 v212, v148, v212
	v_add_f32_e32 v212, v149, v212
	v_add_f32_e32 v211, v211, v212
	s_waitcnt lgkmcnt(2)
	v_mfma_f32_32x32x16_bf16 v[80:95], v[240:243], v[244:247], v[80:95]
	ds_read_b128 v[240:243], v181
	v_mov_b32_e32 v212, v211
	v_add_u32_e32 v194, s31, v183
	s_waitcnt vmcnt(4)
	ds_write_b128 v194, v[140:143]
	v_add_u32_e32 v194, s31, v184
	s_add_i32 s73, s73, 2
	s_cmp_ge_u32 s73, s45
	s_waitcnt vmcnt(2)
	ds_write_b128 v194, v[144:147]
	s_cselect_b64 s[28:29], -1, 0
	ds_write_b128 v185, v[136:139] offset:36864
	v_mfma_f32_32x32x16_bf16 v[64:79], v[248:251], v[244:247], v[64:79]
	ds_read_b128 v[248:251], v187 offset:12288
	ds_read_b128 v[244:247], v189 offset:24576
	s_waitcnt vmcnt(1)
	ds_write_b128 v185, v[132:135] offset:49152
	s_and_b64 vcc, exec, s[28:29]
	s_waitcnt vmcnt(0)
	ds_write_b128 v186, v[128:131] offset:36864
	s_waitcnt lgkmcnt(7)
	v_mfma_f32_32x32x16_bf16 v[80:95], v[232:235], v[240:243], v[80:95]
	ds_read_b128 v[232:235], v179
	s_cbranch_vccnz .Lattn_noloadp
	v_add_co_u32_e32 v128, vcc, 0xfffe0000, v168
	s_nop 1
	v_addc_co_u32_e32 v129, vcc, -1, v169, vcc
	global_load_dwordx4 v[140:143], v[128:129], off
	global_load_dwordx4 v[136:139], v[128:129], off offset:-256
	global_load_dwordx4 v[144:147], v[168:169], off
	global_load_dwordx4 v[132:135], v[168:169], off offset:-256
	s_nop 0
	global_load_dwordx4 v[128:131], v[166:167], off
; __device__ __forceinline__ void finishSM(f32x16& p0, f32x16& p1, float alpha, float& l_reg, bf16x8& pa0, bf16x8& pa1, bf16x8& pa2, bf16x8& pa3) {
;     ...
;   PK4(p0, 0, pa0); PK4(p0, 8, pa1); PK4(p1, 0, pa2); PK4(p1, 8, pa3);
;     ...
; }
; __device__ __forceinline__ void qkt(f32x16& p0, f32x16& p1, const char* Ks, const bf16x8* qr, const char* qrl, int r32, int hi) {
;   p0 = f32x16{}; p1 = f32x16{};
; #pragma unroll
;   for (int d0 = 0; d0 < 8; ++d0) { int cb = (d0 * 16 + hi * 8) * 2;
;     bf16x8 b0 = *reinterpret_cast<const bf16x8*>(Ks + KSWZ(r32, cb));
;     bf16x8 b1 = *reinterpret_cast<const bf16x8*>(Ks + KSWZ(32 + r32, cb));
;     p0 = __builtin_amdgcn_mfma_f32_32x32x16_bf16(b0, qr[d0], p0, 0, 0, 0);
;     p1 = __builtin_amdgcn_mfma_f32_32x32x16_bf16(b1, qr[d0], p1, 0, 0, 0); }
; #pragma unroll
;   for (int d0 = 8; d0 < 12; ++d0) { int cb = (d0 * 16 + hi * 8) * 2;
;     bf16x8 b0 = *reinterpret_cast<const bf16x8*>(Ks + KSWZ(r32, cb));
;     bf16x8 b1 = *reinterpret_cast<const bf16x8*>(Ks + KSWZ(32 + r32, cb));
;     bf16x8 qf = *reinterpret_cast<const bf16x8*>(qrl + (((2 * (d0 - 8) + hi) ^ ((r32 >> 1) & 7)) << 4));
;     p0 = __builtin_amdgcn_mfma_f32_32x32x16_bf16(b0, qf, p0, 0, 0, 0);
;     p1 = __builtin_amdgcn_mfma_f32_32x32x16_bf16(b1, qf, p1, 0, 0, 0); }
; }
; __device__ __forceinline__ int v_st(int k, int c) { const int kk = (k & ~0xC) | ((k & 4) << 1) | ((k & 8) >> 1); return ((kk >> 3) * 4 + (c >> 5)) * 512 + ((kk & 7) * 32 + (c & 31)) * 2; }
; __device__ __forceinline__ int v_rd_base(int lane) { return ((lane & 3) << 3) | (((lane >> 2) & 3) << 6) | (((lane >> 4) & 1) << 5) | (((lane >> 5) & 1) << 8); }
; template <int OFF> __device__ __forceinline__ s16x4 tr_read(int vb) {
;   s16x4 r; asm volatile("ds_read_b64_tr_b16 %0, %1 offset:%2" : "=&v"(r) : "v"(vb), "i"(OFF) : "memory"); return r;
; }
; template <int D0> __device__ __forceinline__ void pv_one(f32x16& od, int vb, bf16x8 pa0, bf16x8 pa1, bf16x8 pa2, bf16x8 pa3) {
;   const s16x4 l0 = tr_read<v_rd_off(D0, 0, 0)>(vb), h0 = tr_read<v_rd_off(D0, 0, 1)>(vb), l1 = tr_read<v_rd_off(D0, 1, 0)>(vb), h1 = tr_read<v_rd_off(D0, 1, 1)>(vb);
;   const s16x4 l2 = tr_read<v_rd_off(D0, 2, 0)>(vb), h2 = tr_read<v_rd_off(D0, 2, 1)>(vb), l3 = tr_read<v_rd_off(D0, 3, 0)>(vb), h3 = tr_read<v_rd_off(D0, 3, 1)>(vb);
;   asm volatile("s_waitcnt lgkmcnt(0)" ::: "memory"); SBAR();
.Lattn_noloadp:
	v_mfma_f32_32x32x16_bf16 v[64:79], v[236:239], v[240:243], v[64:79]
	ds_read_b128 v[236:239], v188 offset:12288
	ds_read_b128 v[240:243], v190 offset:24576
	v_cvt_pk_bf16_f32 v158, v158, v159
	v_cvt_pk_bf16_f32 v159, v156, v157
	v_permlane32_swap_b32_e32 v211, v212
	v_cvt_pk_bf16_f32 v156, v162, v163
	v_cvt_pk_bf16_f32 v157, v160, v161
	v_cvt_pk_bf16_f32 v160, v154, v155
	s_waitcnt lgkmcnt(2)
	v_mfma_f32_32x32x16_bf16 v[80:95], v[248:251], v[232:235], v[80:95]
	ds_read_b128 v[248:251], v177
	v_cvt_pk_bf16_f32 v161, v152, v153
	v_cvt_pk_bf16_f32 v162, v150, v151
	v_cvt_pk_bf16_f32 v163, v148, v149
	v_add_f32_e32 v211, v211, v212
	v_cvt_pk_bf16_f32 v148, v225, v228
	v_cvt_pk_bf16_f32 v149, v226, v229
	v_mfma_f32_32x32x16_bf16 v[64:79], v[244:247], v[232:235], v[64:79]
	v_cvt_pk_bf16_f32 v150, v227, v230
	v_cvt_pk_bf16_f32 v151, v223, v224
	v_cvt_pk_bf16_f32 v152, v219, v221
	v_cvt_pk_bf16_f32 v153, v220, v222
	v_cvt_pk_bf16_f32 v154, v215, v217
	v_cvt_pk_bf16_f32 v155, v216, v218
	s_waitcnt lgkmcnt(0)
	v_mfma_f32_32x32x16_bf16 v[80:95], v[236:239], v[248:251], v[80:95]
	v_fma_f32 v176, v214, v176, v211
	v_mfma_f32_32x32x16_bf16 v[64:79], v[240:243], v[248:251], v[64:79]
	v_lshl_add_u32 v231, s76, 14, v178
	ds_read_b64_tr_b16 v[232:233], v231 offset:0
	ds_read_b64_tr_b16 v[234:235], v231 offset:2048
	ds_read_b64_tr_b16 v[236:237], v231 offset:512
	ds_read_b64_tr_b16 v[238:239], v231 offset:2560
	ds_read_b64_tr_b16 v[240:241], v231 offset:1024
	ds_read_b64_tr_b16 v[242:243], v231 offset:3072
	ds_read_b64_tr_b16 v[248:249], v231 offset:1536
	ds_read_b64_tr_b16 v[250:251], v231 offset:3584
	ds_read_b64_tr_b16 v[244:245], v231 offset:4096
	ds_read_b64_tr_b16 v[246:247], v231 offset:6144
	s_mov_b64 s[100:101], 0x4000
	v_lshl_add_u64 v[166:167], v[166:167], 0, s[100:101]
	v_lshl_add_u64 v[168:169], v[168:169], 0, s[10:11]
	v_max3_f32 v194, v80, v81, v82
	v_max3_f32 v195, v64, v65, v66
	s_waitcnt lgkmcnt(6)
	v_mfma_f32_32x32x16_bf16 v[32:47], v[148:151], v[232:235], v[32:47]
	ds_read_b64_tr_b16 v[232:233], v231 offset:4608
	ds_read_b64_tr_b16 v[234:235], v231 offset:6656
	v_max3_f32 v194, v194, v83, v84
	v_max3_f32 v195, v195, v67, v68
	v_max3_f32 v194, v194, v85, v86
	v_max3_f32 v195, v195, v69, v70
	v_mfma_f32_32x32x16_bf16 v[48:63], v[148:151], v[236:239], v[48:63]
	ds_read_b64_tr_b16 v[236:237], v231 offset:5120
	ds_read_b64_tr_b16 v[238:239], v231 offset:7168
	v_max3_f32 v194, v194, v87, v88
	v_max3_f32 v195, v195, v71, v72
	v_max3_f32 v194, v194, v89, v90
	v_max3_f32 v195, v195, v73, v74
	s_waitcnt lgkmcnt(6)
	v_mfma_f32_32x32x16_bf16 v[16:31], v[148:151], v[240:243], v[16:31]
	ds_read_b64_tr_b16 v[240:241], v231 offset:5632
	ds_read_b64_tr_b16 v[242:243], v231 offset:7680
	v_max3_f32 v194, v194, v91, v92
	v_max3_f32 v195, v195, v75, v76
	v_max3_f32 v194, v194, v93, v94
	v_max3_f32 v195, v195, v77, v78
	v_mfma_f32_32x32x16_bf16 v[0:15], v[148:151], v[248:251], v[0:15]
	ds_read_b64_tr_b16 v[248:249], v231 offset:8192
	ds_read_b64_tr_b16 v[250:251], v231 offset:10240
	v_max3_f32 v194, v194, v95, v195
	v_max_f32_e32 v194, v194, v79
	v_mov_b32_e32 v195, v194
	s_nop 1
	s_waitcnt lgkmcnt(6)
	v_mfma_f32_32x32x16_bf16 v[32:47], v[152:155], v[244:247], v[32:47]
	ds_read_b64_tr_b16 v[244:245], v231 offset:8704
	ds_read_b64_tr_b16 v[246:247], v231 offset:10752
	v_permlane32_swap_b32_e32 v194, v195
	v_max_f32_e32 v194, v194, v195
	v_sub_f32_e32 v195, v194, v210
	v_cmp_ge_f32_e32 vcc, s15, v195
	v_mfma_f32_32x32x16_bf16 v[48:63], v[152:155], v[232:235], v[48:63]
	ds_read_b64_tr_b16 v[232:233], v231 offset:9216
	ds_read_b64_tr_b16 v[234:235], v231 offset:11264
	s_cmp_eq_u64 vcc, exec
	s_cselect_b64 s[40:41], -1, 0
	s_cbranch_scc1 .Lattn_fast2p
	v_max_f32_e32 v194, v210, v194
	v_sub_f32_e32 v195, v210, v194
	v_mul_f32_e32 v195, 0x3dd53b94, v195
	v_exp_f32_e32 v213, v195
	v_mov_b32_e32 v210, v194
	s_branch .Lattn_join2p

; __device__ __forceinline__ void finishSM(f32x16& p0, f32x16& p1, float alpha, float& l_reg, bf16x8& pa0, bf16x8& pa1, bf16x8& pa2, bf16x8& pa3) {
; #pragma unroll
;   for (int r = 0; r < 16; ++r) p1[r] = __builtin_amdgcn_exp2f(p1[r]);
;   float ps = 0;
; #pragma unroll
;   for (int r = 0; r < 16; ++r) ps += p0[r];
; #pragma unroll
;   for (int r = 0; r < 16; ++r) ps += p1[r];
;   { auto rr = __builtin_amdgcn_permlane32_swap(__float_as_uint(ps), __float_as_uint(ps), false, false);
;     ps = __uint_as_float(rr[0]) + __uint_as_float(rr[1]); }
;   l_reg = l_reg * alpha + ps;
;     ...
;   PK4(p0, 0, pa0); PK4(p0, 8, pa1); PK4(p1, 0, pa2); PK4(p1, 8, pa3);
;     ...
; }
; __device__ __forceinline__ void qkt(f32x16& p0, f32x16& p1, const char* Ks, const bf16x8* qr, const char* qrl, int r32, int hi) {
;   p0 = f32x16{}; p1 = f32x16{};
; #pragma unroll
;   for (int d0 = 0; d0 < 8; ++d0) { int cb = (d0 * 16 + hi * 8) * 2;
;     bf16x8 b0 = *reinterpret_cast<const bf16x8*>(Ks + KSWZ(r32, cb));
;     bf16x8 b1 = *reinterpret_cast<const bf16x8*>(Ks + KSWZ(32 + r32, cb));
;     p0 = __builtin_amdgcn_mfma_f32_32x32x16_bf16(b0, qr[d0], p0, 0, 0, 0);
;     p1 = __builtin_amdgcn_mfma_f32_32x32x16_bf16(b1, qr[d0], p1, 0, 0, 0); }
; #pragma unroll
;   for (int d0 = 8; d0 < 12; ++d0) { int cb = (d0 * 16 + hi * 8) * 2;
;     bf16x8 b0 = *reinterpret_cast<const bf16x8*>(Ks + KSWZ(r32, cb));
;     bf16x8 b1 = *reinterpret_cast<const bf16x8*>(Ks + KSWZ(32 + r32, cb));
;     bf16x8 qf = *reinterpret_cast<const bf16x8*>(qrl + (((2 * (d0 - 8) + hi) ^ ((r32 >> 1) & 7)) << 4));
;     p0 = __builtin_amdgcn_mfma_f32_32x32x16_bf16(b0, qf, p0, 0, 0, 0);
;     p1 = __builtin_amdgcn_mfma_f32_32x32x16_bf16(b1, qf, p1, 0, 0, 0); }
; }
.Lattn_steady:
	s_waitcnt lgkmcnt(3)
	v_mfma_f32_32x32x16_bf16 v[80:95], v[236:239], v[124:127], 0
	ds_read_b128 v[236:239], v206 offset:49152
	v_exp_f32_e32 v225, v225
	v_exp_f32_e32 v228, v228
	v_exp_f32_e32 v226, v226
	v_mfma_f32_32x32x16_bf16 v[64:79], v[240:243], v[124:127], 0
	ds_read_b128 v[240:243], v208 offset:36864
	v_add_f32_e32 v211, v225, v228
	v_exp_f32_e32 v229, v229
	v_add_f32_e32 v211, v226, v211
	v_exp_f32_e32 v227, v227
	s_waitcnt lgkmcnt(3)
	v_mfma_f32_32x32x16_bf16 v[80:95], v[248:251], v[120:123], v[80:95]
	ds_read_b128 v[248:251], v208 offset:49152
	v_add_f32_e32 v211, v229, v211
	v_exp_f32_e32 v230, v230
	v_add_f32_e32 v211, v227, v211
	v_exp_f32_e32 v223, v223
	v_mfma_f32_32x32x16_bf16 v[64:79], v[244:247], v[120:123], v[64:79]
	ds_read_b128 v[244:247], v207 offset:36864
	v_add_f32_e32 v211, v230, v211
	v_exp_f32_e32 v224, v224
	v_add_f32_e32 v211, v223, v211
	v_exp_f32_e32 v219, v219
	s_waitcnt lgkmcnt(3)
	v_mfma_f32_32x32x16_bf16 v[80:95], v[232:235], v[116:119], v[80:95]
	ds_read_b128 v[232:235], v207 offset:49152
	v_add_f32_e32 v211, v224, v211
	v_exp_f32_e32 v221, v221
	v_add_f32_e32 v211, v219, v211
	v_exp_f32_e32 v220, v220
	v_mfma_f32_32x32x16_bf16 v[64:79], v[236:239], v[116:119], v[64:79]
	ds_read_b128 v[236:239], v204 offset:36864
	v_add_f32_e32 v211, v221, v211
	v_exp_f32_e32 v222, v222
	v_add_f32_e32 v211, v220, v211
	v_exp_f32_e32 v215, v215
	s_waitcnt lgkmcnt(3)
	v_mfma_f32_32x32x16_bf16 v[80:95], v[240:243], v[112:115], v[80:95]
	ds_read_b128 v[240:243], v204 offset:49152
	v_add_f32_e32 v211, v222, v211
	v_exp_f32_e32 v217, v217
	v_add_f32_e32 v211, v215, v211
	v_exp_f32_e32 v216, v216
	v_mfma_f32_32x32x16_bf16 v[64:79], v[248:251], v[112:115], v[64:79]
	ds_read_b128 v[248:251], v203 offset:36864
	v_add_f32_e32 v211, v217, v211
	v_exp_f32_e32 v218, v218
	v_add_f32_e32 v211, v216, v211
	v_exp_f32_e32 v162, v162
	s_waitcnt lgkmcnt(3)
	v_mfma_f32_32x32x16_bf16 v[80:95], v[244:247], v[108:111], v[80:95]
	ds_read_b128 v[244:247], v203 offset:49152
	v_add_f32_e32 v211, v218, v211
	v_exp_f32_e32 v163, v163
	v_exp_f32_e32 v160, v160
	v_mfma_f32_32x32x16_bf16 v[64:79], v[232:235], v[108:111], v[64:79]
	ds_read_b128 v[232:235], v200 offset:36864
	v_exp_f32_e32 v161, v161
	v_exp_f32_e32 v158, v158
	v_exp_f32_e32 v159, v159
	s_waitcnt lgkmcnt(3)
	v_mfma_f32_32x32x16_bf16 v[80:95], v[236:239], v[104:107], v[80:95]
	ds_read_b128 v[236:239], v200 offset:49152
	v_exp_f32_e32 v156, v156
	v_exp_f32_e32 v157, v157
	v_exp_f32_e32 v154, v154
	v_mfma_f32_32x32x16_bf16 v[64:79], v[240:243], v[104:107], v[64:79]
	ds_read_b128 v[240:243], v191 offset:36864
	v_exp_f32_e32 v155, v155
	v_exp_f32_e32 v152, v152
	v_exp_f32_e32 v153, v153
	s_waitcnt lgkmcnt(3)
	v_mfma_f32_32x32x16_bf16 v[80:95], v[248:251], v[100:103], v[80:95]
	ds_read_b128 v[248:251], v202 offset:49152
	v_exp_f32_e32 v150, v150
	v_exp_f32_e32 v151, v151
	v_exp_f32_e32 v148, v148
	v_mfma_f32_32x32x16_bf16 v[64:79], v[244:247], v[100:103], v[64:79]
	ds_read_b128 v[244:247], v182
	v_exp_f32_e32 v149, v149
	v_add_f32_e32 v212, v162, v163
	v_add_f32_e32 v212, v160, v212
	v_add_f32_e32 v212, v161, v212
	v_add_f32_e32 v212, v158, v212
	s_waitcnt lgkmcnt(3)
	v_mfma_f32_32x32x16_bf16 v[80:95], v[232:235], v[96:99], v[80:95]
	ds_read_b128 v[232:235], v198 offset:36864
	v_add_f32_e32 v212, v159, v212
	v_add_f32_e32 v212, v156, v212
	v_add_f32_e32 v212, v157, v212
	v_add_f32_e32 v212, v154, v212
	v_add_f32_e32 v212, v155, v212
	v_add_f32_e32 v212, v152, v212
	v_mfma_f32_32x32x16_bf16 v[64:79], v[236:239], v[96:99], v[64:79]
	ds_read_b128 v[236:239], v201 offset:49152
	v_add_f32_e32 v212, v153, v212
	v_add_f32_e32 v212, v150, v212
	v_add_f32_e32 v212, v151, v212
	v_add_f32_e32 v212, v148, v212
	v_add_f32_e32 v212, v149, v212
	v_add_f32_e32 v211, v211, v212
	s_waitcnt lgkmcnt(2)
	v_mfma_f32_32x32x16_bf16 v[80:95], v[240:243], v[244:247], v[80:95]
	ds_read_b128 v[240:243], v181
	v_mov_b32_e32 v212, v211
	s_lshl_b32 s19, s18, 14
	v_add_u32_e32 v231, s19, v183
	s_waitcnt vmcnt(0)
	ds_write_b128 v231, v[140:143]
	v_add_u32_e32 v140, s19, v184
	ds_write_b128 v140, v[144:147]
	ds_write_b128 v185, v[136:139] offset:12288
	ds_write_b128 v185, v[132:135] offset:24576
	s_mov_b32 s18, 0xfffa0000
	v_mfma_f32_32x32x16_bf16 v[64:79], v[248:251], v[244:247], v[64:79]
	ds_read_b128 v[248:251], v187 offset:36864
	ds_read_b128 v[244:247], v189 offset:49152
	ds_write_b128 v186, v[128:131] offset:12288
	v_add_co_u32_e32 v128, vcc, s18, v168
	s_mov_b32 s18, 0xfffc0000
	s_nop 0
	v_addc_co_u32_e32 v129, vcc, -1, v169, vcc
	v_add_co_u32_e32 v130, vcc, s18, v168
	s_movk_i32 s18, 0xe000
	s_nop 0
	v_addc_co_u32_e32 v131, vcc, -1, v169, vcc
	global_load_dwordx4 v[140:143], v[128:129], off
	s_waitcnt lgkmcnt(7)
; __device__ __forceinline__ void partialSM(f32x16& p0, f32x16& p1, float& m_reg, float& mn, float& alpha) {
;   constexpr float C = SCALE * 1.4426950408889634f;
;   float pmax = p0[0];
; #pragma unroll
;   for (int r = 1; r < 16; ++r) pmax = fmaxf(pmax, p0[r]);
; #pragma unroll
;   for (int r = 0; r < 16; ++r) pmax = fmaxf(pmax, p1[r]);
;   { auto rr = __builtin_amdgcn_permlane32_swap(__float_as_uint(pmax), __float_as_uint(pmax), false, false);
;     pmax = fmaxf(__uint_as_float(rr[0]), __uint_as_float(rr[1])); }
;   if (__builtin_expect(__all(pmax - m_reg <= THR / SCALE), 1)) { mn = m_reg; alpha = 1.f; }
;   else { mn = fmaxf(m_reg, pmax); alpha = __builtin_amdgcn_exp2f((m_reg - mn) * C); m_reg = mn; }
;   float mnC = -mn * C;
; #pragma unroll
;   for (int r = 0; r < 16; ++r) p0[r] = fmaf(p0[r], C, mnC);
; #pragma unroll
;   for (int r = 0; r < 16; ++r) p1[r] = fmaf(p1[r], C, mnC);
; #pragma unroll
;   for (int r = 0; r < 16; ++r) p0[r] = __builtin_amdgcn_exp2f(p0[r]);
; }
; __device__ __forceinline__ void finishSM(f32x16& p0, f32x16& p1, float alpha, float& l_reg, bf16x8& pa0, bf16x8& pa1, bf16x8& pa2, bf16x8& pa3) {
; #pragma unroll
;   for (int r = 0; r < 16; ++r) p1[r] = __builtin_amdgcn_exp2f(p1[r]);
;   float ps = 0;
; #pragma unroll
;   for (int r = 0; r < 16; ++r) ps += p0[r];
; #pragma unroll
;   for (int r = 0; r < 16; ++r) ps += p1[r];
;   { auto rr = __builtin_amdgcn_permlane32_swap(__float_as_uint(ps), __float_as_uint(ps), false, false);
;     ps = __uint_as_float(rr[0]) + __uint_as_float(rr[1]); }
;   l_reg = l_reg * alpha + ps;
;     ...
;   PK4(p0, 0, pa0); PK4(p0, 8, pa1); PK4(p1, 0, pa2); PK4(p1, 8, pa3);
;     ...
; }
; template <int OFF> __device__ __forceinline__ s16x4 tr_read(int vb) {
;   s16x4 r; asm volatile("ds_read_b64_tr_b16 %0, %1 offset:%2" : "=&v"(r) : "v"(vb), "i"(OFF) : "memory"); return r;
; }
; template <int D0> __device__ __forceinline__ void pv_one(f32x16& od, int vb, bf16x8 pa0, bf16x8 pa1, bf16x8 pa2, bf16x8 pa3) {
;   const s16x4 l0 = tr_read<v_rd_off(D0, 0, 0)>(vb), h0 = tr_read<v_rd_off(D0, 0, 1)>(vb), l1 = tr_read<v_rd_off(D0, 1, 0)>(vb), h1 = tr_read<v_rd_off(D0, 1, 1)>(vb);
;   const s16x4 l2 = tr_read<v_rd_off(D0, 2, 0)>(vb), h2 = tr_read<v_rd_off(D0, 2, 1)>(vb), l3 = tr_read<v_rd_off(D0, 3, 0)>(vb), h3 = tr_read<v_rd_off(D0, 3, 1)>(vb);
;   asm volatile("s_waitcnt lgkmcnt(0)" ::: "memory"); SBAR();
	v_mfma_f32_32x32x16_bf16 v[80:95], v[232:235], v[240:243], v[80:95]
	ds_read_b128 v[232:235], v179
	global_load_dwordx4 v[136:139], v[128:129], off offset:-256
	global_load_dwordx4 v[144:147], v[130:131], off
	global_load_dwordx4 v[132:135], v[130:131], off offset:-256
	v_add_co_u32_e32 v128, vcc, s18, v166
	s_nop 1
	v_addc_co_u32_e32 v129, vcc, -1, v167, vcc
	global_load_dwordx4 v[128:131], v[128:129], off
	v_mfma_f32_32x32x16_bf16 v[64:79], v[236:239], v[240:243], v[64:79]
	ds_read_b128 v[236:239], v188 offset:36864
	ds_read_b128 v[240:243], v190 offset:49152
	v_cvt_pk_bf16_f32 v158, v158, v159
	v_cvt_pk_bf16_f32 v159, v156, v157
	v_permlane32_swap_b32_e32 v211, v212
	v_cvt_pk_bf16_f32 v156, v162, v163
	v_cvt_pk_bf16_f32 v157, v160, v161
	v_cvt_pk_bf16_f32 v160, v154, v155
	s_waitcnt lgkmcnt(2)
	v_mfma_f32_32x32x16_bf16 v[80:95], v[248:251], v[232:235], v[80:95]
	ds_read_b128 v[248:251], v177
	v_cvt_pk_bf16_f32 v161, v152, v153
	v_cvt_pk_bf16_f32 v162, v150, v151
	v_cvt_pk_bf16_f32 v163, v148, v149
	v_add_f32_e32 v211, v211, v212
	v_cvt_pk_bf16_f32 v148, v225, v228
	v_cvt_pk_bf16_f32 v149, v226, v229
	v_mfma_f32_32x32x16_bf16 v[64:79], v[244:247], v[232:235], v[64:79]
	v_cvt_pk_bf16_f32 v150, v227, v230
	v_cvt_pk_bf16_f32 v151, v223, v224
	v_cvt_pk_bf16_f32 v152, v219, v221
	v_cvt_pk_bf16_f32 v153, v220, v222
	v_cvt_pk_bf16_f32 v154, v215, v217
	v_cvt_pk_bf16_f32 v155, v216, v218
	s_waitcnt lgkmcnt(0)
	v_mfma_f32_32x32x16_bf16 v[80:95], v[236:239], v[248:251], v[80:95]
	v_fma_f32 v176, v209, v176, v211
	v_mfma_f32_32x32x16_bf16 v[64:79], v[240:243], v[248:251], v[64:79]
	s_lshl_b32 s31, s30, 14
	v_add_u32_e32 v180, s31, v178
	ds_read_b64_tr_b16 v[232:233], v180 offset:0
	ds_read_b64_tr_b16 v[234:235], v180 offset:2048
	ds_read_b64_tr_b16 v[236:237], v180 offset:512
	ds_read_b64_tr_b16 v[238:239], v180 offset:2560
	ds_read_b64_tr_b16 v[240:241], v180 offset:1024
	ds_read_b64_tr_b16 v[242:243], v180 offset:3072
	ds_read_b64_tr_b16 v[248:249], v180 offset:1536
	ds_read_b64_tr_b16 v[250:251], v180 offset:3584
	ds_read_b64_tr_b16 v[244:245], v180 offset:4096
	ds_read_b64_tr_b16 v[246:247], v180 offset:6144
	v_max3_f32 v194, v80, v81, v82
	v_max3_f32 v195, v64, v65, v66
	v_max3_f32 v194, v194, v83, v84
	v_max3_f32 v195, v195, v67, v68
	s_waitcnt lgkmcnt(6)
	v_mfma_f32_32x32x16_bf16 v[32:47], v[148:151], v[232:235], v[32:47]
	ds_read_b64_tr_b16 v[232:233], v180 offset:4608
	ds_read_b64_tr_b16 v[234:235], v180 offset:6656
	v_max3_f32 v194, v194, v85, v86
	v_max3_f32 v195, v195, v69, v70
	v_max3_f32 v194, v194, v87, v88
	v_max3_f32 v195, v195, v71, v72
	v_mfma_f32_32x32x16_bf16 v[48:63], v[148:151], v[236:239], v[48:63]
	ds_read_b64_tr_b16 v[236:237], v180 offset:5120
	ds_read_b64_tr_b16 v[238:239], v180 offset:7168
	v_max3_f32 v194, v194, v89, v90
	v_max3_f32 v195, v195, v73, v74
	v_max3_f32 v194, v194, v91, v92
	v_max3_f32 v195, v195, v75, v76
	s_waitcnt lgkmcnt(6)
	v_mfma_f32_32x32x16_bf16 v[16:31], v[148:151], v[240:243], v[16:31]
	ds_read_b64_tr_b16 v[240:241], v180 offset:5632
	ds_read_b64_tr_b16 v[242:243], v180 offset:7680
	v_max3_f32 v194, v194, v93, v94
	v_max3_f32 v195, v195, v77, v78
	v_max3_f32 v194, v194, v95, v195
	v_max_f32_e32 v194, v194, v79
	v_mfma_f32_32x32x16_bf16 v[0:15], v[148:151], v[248:251], v[0:15]
	ds_read_b64_tr_b16 v[248:249], v180 offset:8192
	ds_read_b64_tr_b16 v[250:251], v180 offset:10240
	v_mov_b32_e32 v195, v194
	s_nop 1
	v_permlane32_swap_b32_e32 v194, v195
	v_max_f32_e32 v194, v194, v195
	s_waitcnt lgkmcnt(6)
	v_mfma_f32_32x32x16_bf16 v[32:47], v[152:155], v[244:247], v[32:47]
	ds_read_b64_tr_b16 v[244:245], v180 offset:8704
	ds_read_b64_tr_b16 v[246:247], v180 offset:10752
	v_sub_f32_e32 v195, v194, v210
	v_cmp_ge_f32_e32 vcc, s15, v195
	v_mfma_f32_32x32x16_bf16 v[48:63], v[152:155], v[232:235], v[48:63]
	ds_read_b64_tr_b16 v[232:233], v180 offset:9216
	ds_read_b64_tr_b16 v[234:235], v180 offset:11264
	s_cmp_eq_u64 vcc, exec
	s_cselect_b64 s[40:41], -1, 0
	s_cbranch_scc1 .Lattn_fast1
	v_max_f32_e32 v194, v210, v194
	v_sub_f32_e32 v195, v210, v194
	v_mul_f32_e32 v195, 0x3dd53b94, v195
	v_exp_f32_e32 v214, v195
	v_mov_b32_e32 v210, v194
	s_branch .Lattn_join1
